# P1 in-projection: first K-tile counted waits of a unit no longer wait for the previous unit's 16 epilogue stores (vmcnt 26 / 10 by flag), on top of peeled K-loops + hand EpiGlu
# baseline (speedup 1.0000x reference)
.LBB0_742:
	s_lshl_b32 s26, s48, 4
	s_ashr_i32 s27, s26, 31
	s_lshl_b64 s[26:27], s[26:27], 2
	s_waitcnt vmcnt(0)
	v_bfe_u32 v156, v17, 4, 2
	s_waitcnt lgkmcnt(0)
	s_add_u32 s44, s22, s26
	v_and_b32_e32 v1, 15, v17
	v_lshlrev_b32_e32 v18, 4, v156
	v_lshlrev_b32_e32 v17, 2, v17
	s_addc_u32 s45, s23, s27
	s_and_b32 s15, s25, 3
	v_lshl_or_b32 v18, v1, 6, v18
	s_lshl_b32 s17, s34, 13
	v_and_b32_e32 v17, 32, v17
	s_add_i32 m0, s36, 0x18000
	v_lshl_add_u64 v[10:11], v[10:11], 0, s[96:97]
	s_lshl_b32 s66, s34, 6
	v_bitop3_b32 v19, v18, s17, v17 bitop3:0xde
	s_lshl_b32 s17, s15, 5
	s_lshl_b32 s22, s15, 12
	s_waitcnt vmcnt(2)
	s_barrier
	global_load_lds_dwordx4 v[10:11], off
	v_lshl_add_u64 v[8:9], v[8:9], 0, s[96:97]
	s_add_i32 m0, s36, 0x1a000
	s_add_i32 s67, s36, 0x8000
	s_add_i32 s68, s36, 0xa000
	v_bitop3_b32 v157, v18, s22, v17 bitop3:0xde
	global_load_lds_dwordx4 v[8:9], off
	v_lshl_add_u64 v[4:5], v[4:5], 0, s[96:97]
	s_mov_b32 m0, s67
	s_add_u32 s22, s20, 0x40080
	global_load_lds_dwordx4 v[4:5], off
	v_lshl_add_u64 v[4:5], v[6:7], 0, s[96:97]
	s_mov_b32 m0, s68
	s_addc_u32 s23, s21, 0
	global_load_lds_dwordx4 v[4:5], off
	s_add_i32 m0, s36, 0x1c000
	v_lshl_add_u64 v[4:5], s[22:23], 0, v[134:135]
	global_load_lds_dwordx4 v[4:5], off
	v_lshl_add_u64 v[4:5], s[22:23], 0, v[138:139]
	s_add_i32 m0, s36, 0x1e000
	s_cmpk_lt_u32 s24, 0x100
	global_load_lds_dwordx4 v[4:5], off
	s_mov_b32 s88, s48
	s_cselect_b64 s[46:47], -1, 0
	s_add_u32 s48, s6, 0x4c0000
	v_lshlrev_b32_e32 v4, 14, v2
	s_addc_u32 s49, s7, 0
	s_and_b32 s22, s24, 0xffffff00
	s_lshl_b32 s23, s15, 6
	v_and_b32_e32 v4, 0xffff8000, v4
	s_or_b32 s69, s23, s22
	v_lshl_add_u32 v4, v12, 11, v4
	v_and_b32_e32 v2, 1, v2
	s_add_u32 s50, s6, 0x100000
	v_lshl_or_b32 v2, v2, 6, v4
	s_addc_u32 s51, s7, 0
	s_lshl_b32 s70, s34, 8
	v_lshl_add_u32 v140, v13, 1, v2
	v_lshlrev_b32_e32 v2, 14, v14
	s_add_i32 s70, s70, 0x20000
	s_lshl_b32 s71, s15, 3
	v_and_b32_e32 v2, 0xffff8000, v2
	s_waitcnt vmcnt(6)
	s_cmp_eq_u32 s15, 0
	v_lshl_add_u32 v2, v15, 11, v2
	v_and_b32_e32 v4, 1, v14
	s_cselect_b64 s[52:53], -1, 0
	s_add_u32 s73, s6, 0xb0a0000
	v_lshl_or_b32 v2, v4, 6, v2
	s_mov_b32 s72, 0
	s_addc_u32 s74, s7, 0
	s_or_b32 s75, s71, 1
	s_or_b32 s76, s71, 2
	s_or_b32 s77, s71, 3
	s_or_b32 s78, s71, 4
	s_or_b32 s79, s71, 5
	s_or_b32 s80, s71, 6
	s_or_b32 s81, s71, 7
	v_mov_b32_e32 v141, v3
	v_lshl_add_u32 v142, v16, 1, v2
	v_mov_b32_e32 v143, v3
	v_add_u32_e32 v158, 0, v19
	s_lshl_b32 s82, s17, 1
	s_barrier
	s_mov_b32 s100, 0
	s_branch .LBB0_745

.LBB0_751:
	v_lshlrev_b32_e32 v2, 4, v0
	s_lshl_b32 s22, s16, 14
	s_add_u32 s22, s50, s22
	s_addc_u32 s23, s51, 0
	v_readfirstlane_b32 s57, v2
	s_nop 3
	s_add_i32 m0, s57, 0x20400
	s_nop 0
	global_load_lds_dwordx4 v2, s[22:23]
	v_add_u32_e32 v2, 0x2000, v2
	s_add_i32 m0, s57, 0x22400
	s_nop 0
	global_load_lds_dwordx4 v2, s[22:23]
	s_ashr_i32 s57, s56, 31
	s_lshl_b64 s[22:23], s[56:57], 19
	s_add_u32 s58, s28, s22
	s_addc_u32 s59, s29, s23
	s_and_b64 s[22:23], s[38:39], exec
	s_cselect_b32 s15, s59, s19
	s_cselect_b32 s17, s58, s18
	s_ashr_i32 s55, s54, 31
	s_lshl_b64 s[22:23], s[54:55], 19
	s_add_u32 s60, s30, s22
	s_addc_u32 s61, s31, s23
	s_and_b64 s[22:23], s[38:39], exec
	s_cselect_b32 s24, s61, s21
	s_cselect_b32 s25, s60, s20
	s_add_u32 s18, s18, 0x40080
	s_addc_u32 s19, s19, 0
	s_add_u32 s26, s20, 0x100
	s_addc_u32 s27, s21, 0
	s_mov_b32 s40, -2
	s_waitcnt lgkmcnt(0)
.Lk1_peel:
	s_add_u32 s20, s18, 0xfffc0080
	s_addc_u32 s21, s19, -1
	s_add_i32 s41, 0, 0x10000
	s_cmp_eq_u32 s40, 12
	s_cselect_b32 s23, s15, s21
	s_cselect_b32 s22, s17, s20
	v_add_u32_e32 v2, s41, v157
	s_cselect_b32 s21, s24, s27
	s_cselect_b32 s20, s25, s26
	s_add_i32 s55, 0, 0x14000
	ds_read_b128 v[144:147], v2
	ds_read_b128 v[148:151], v2 offset:1024
	ds_read_b128 v[152:155], v2 offset:2048
	ds_read_b128 v[160:163], v2 offset:3072
	v_add_u32_e32 v2, s55, v157
	ds_read_b128 v[164:167], v2
	ds_read_b128 v[168:171], v2 offset:1024
	ds_read_b128 v[172:175], v2 offset:2048
	ds_read_b128 v[176:179], v2 offset:3072
	v_lshl_add_u64 v[234:235], s[18:19], 0, v[140:141]
	s_add_i32 m0, s36, 0xc000
	ds_read_b128 v[180:183], v158
	ds_read_b128 v[184:187], v158 offset:1024
	ds_read_b128 v[188:191], v158 offset:2048
	ds_read_b128 v[192:195], v158 offset:3072
	ds_read_b128 v[206:209], v158 offset:4096
	ds_read_b128 v[210:213], v158 offset:5120
	ds_read_b128 v[214:217], v158 offset:6144
	ds_read_b128 v[218:221], v158 offset:7168
	global_load_lds_dwordx4 v[234:235], off
	v_lshl_add_u64 v[234:235], s[18:19], 0, v[142:143]
	s_add_i32 m0, s36, 0xe000
	s_nop 0
	global_load_lds_dwordx4 v[234:235], off
	s_cmp_eq_u32 s100, 1
	s_cbranch_scc1 .Lk1_w26b
	s_waitcnt vmcnt(10)
	s_branch .Lk1_wjb
.Lk1_w26b:
	s_waitcnt vmcnt(26)
.Lk1_wjb:
	s_waitcnt lgkmcnt(0)
	s_barrier
	s_waitcnt lgkmcnt(0)
	v_mfma_f32_16x16x32_bf16 v[120:123], v[144:147], v[180:183], 0
	v_mfma_f32_16x16x32_bf16 v[116:119], v[152:155], v[180:183], 0
	v_mfma_f32_16x16x32_bf16 v[104:107], v[144:147], v[188:191], 0
	v_mfma_f32_16x16x32_bf16 v[100:103], v[152:155], v[188:191], 0
	v_mfma_f32_16x16x32_bf16 v[88:91], v[144:147], v[206:209], 0
	v_mfma_f32_16x16x32_bf16 v[84:87], v[152:155], v[206:209], 0
	v_mfma_f32_16x16x32_bf16 v[72:75], v[144:147], v[214:217], 0
	v_mfma_f32_16x16x32_bf16 v[68:71], v[152:155], v[214:217], 0
	v_mfma_f32_16x16x32_bf16 v[120:123], v[148:151], v[184:187], v[120:123]
	v_mfma_f32_16x16x32_bf16 v[116:119], v[160:163], v[184:187], v[116:119]
	v_mfma_f32_16x16x32_bf16 v[104:107], v[148:151], v[192:195], v[104:107]
	v_mfma_f32_16x16x32_bf16 v[100:103], v[160:163], v[192:195], v[100:103]
	v_mfma_f32_16x16x32_bf16 v[88:91], v[148:151], v[210:213], v[88:91]
	v_mfma_f32_16x16x32_bf16 v[84:87], v[160:163], v[210:213], v[84:87]
	v_mfma_f32_16x16x32_bf16 v[72:75], v[148:151], v[218:221], v[72:75]
	v_mfma_f32_16x16x32_bf16 v[68:71], v[160:163], v[218:221], v[68:71]
	v_mfma_f32_16x16x32_bf16 v[128:131], v[164:167], v[180:183], 0
	v_mfma_f32_16x16x32_bf16 v[124:127], v[172:175], v[180:183], 0
	v_mfma_f32_16x16x32_bf16 v[112:115], v[164:167], v[188:191], 0
	v_mfma_f32_16x16x32_bf16 v[108:111], v[172:175], v[188:191], 0
	v_mfma_f32_16x16x32_bf16 v[96:99], v[164:167], v[206:209], 0
	v_mfma_f32_16x16x32_bf16 v[92:95], v[172:175], v[206:209], 0
	v_mfma_f32_16x16x32_bf16 v[80:83], v[164:167], v[214:217], 0
	v_mfma_f32_16x16x32_bf16 v[76:79], v[172:175], v[214:217], 0
	v_mfma_f32_16x16x32_bf16 v[128:131], v[168:171], v[184:187], v[128:131]
	v_mfma_f32_16x16x32_bf16 v[124:127], v[176:179], v[184:187], v[124:127]
	v_mfma_f32_16x16x32_bf16 v[112:115], v[168:171], v[192:195], v[112:115]
	v_mfma_f32_16x16x32_bf16 v[108:111], v[176:179], v[192:195], v[108:111]
	v_mfma_f32_16x16x32_bf16 v[96:99], v[168:171], v[210:213], v[96:99]
	v_mfma_f32_16x16x32_bf16 v[92:95], v[176:179], v[210:213], v[92:95]
	v_mfma_f32_16x16x32_bf16 v[80:83], v[168:171], v[218:221], v[80:83]
	v_mfma_f32_16x16x32_bf16 v[76:79], v[176:179], v[218:221], v[76:79]
	s_barrier
	s_add_i32 s41, s41, s35
	v_lshl_add_u64 v[234:235], s[20:21], 0, v[134:135]
	s_mov_b32 m0, s41
	ds_read_b128 v[180:183], v158 offset:16384
	ds_read_b128 v[184:187], v158 offset:17408
	ds_read_b128 v[188:191], v158 offset:18432
	ds_read_b128 v[192:195], v158 offset:19456
	ds_read_b128 v[206:209], v158 offset:20480
	ds_read_b128 v[210:213], v158 offset:21504
	ds_read_b128 v[214:217], v158 offset:22528
	ds_read_b128 v[218:221], v158 offset:23552
	global_load_lds_dwordx4 v[234:235], off
	s_add_i32 m0, s41, 0x2000
	s_add_u32 s42, s20, 0x40000
	v_lshl_add_u64 v[236:237], s[20:21], 0, v[138:139]
	s_addc_u32 s43, s21, 0
	s_add_i32 s41, s55, s35
	global_load_lds_dwordx4 v[236:237], off
	v_lshl_add_u64 v[238:239], s[42:43], 0, v[134:135]
	s_mov_b32 m0, s41
	v_lshl_add_u64 v[240:241], s[22:23], 0, v[136:137]
	global_load_lds_dwordx4 v[238:239], off
	v_lshl_add_u64 v[238:239], s[42:43], 0, v[138:139]
	s_add_i32 m0, s41, 0x2000
	s_nop 0
	global_load_lds_dwordx4 v[238:239], off
	v_lshl_add_u64 v[238:239], s[22:23], 0, v[132:133]
	s_mov_b32 m0, s36
	s_nop 0
	global_load_lds_dwordx4 v[238:239], off
	s_mov_b32 m0, s37
	s_nop 0
	global_load_lds_dwordx4 v[240:241], off
	s_cmp_eq_u32 s100, 1
	s_cbranch_scc1 .Lk1_w26a
	s_waitcnt vmcnt(10)
	s_branch .Lk1_wja

.Lk1_wja:
	s_waitcnt lgkmcnt(0)
	s_barrier
	s_waitcnt lgkmcnt(0)
	v_mfma_f32_16x16x32_bf16 v[56:59], v[144:147], v[180:183], 0
	v_mfma_f32_16x16x32_bf16 v[52:55], v[152:155], v[180:183], 0
	v_mfma_f32_16x16x32_bf16 v[40:43], v[144:147], v[188:191], 0
	v_mfma_f32_16x16x32_bf16 v[36:39], v[152:155], v[188:191], 0
	v_mfma_f32_16x16x32_bf16 v[24:27], v[144:147], v[206:209], 0
	v_mfma_f32_16x16x32_bf16 v[20:23], v[152:155], v[206:209], 0
	v_mfma_f32_16x16x32_bf16 v[8:11], v[144:147], v[214:217], 0
	v_mfma_f32_16x16x32_bf16 v[4:7], v[152:155], v[214:217], 0
	v_mfma_f32_16x16x32_bf16 v[56:59], v[148:151], v[184:187], v[56:59]
	v_mfma_f32_16x16x32_bf16 v[52:55], v[160:163], v[184:187], v[52:55]
	v_mfma_f32_16x16x32_bf16 v[40:43], v[148:151], v[192:195], v[40:43]
	v_mfma_f32_16x16x32_bf16 v[36:39], v[160:163], v[192:195], v[36:39]
	v_mfma_f32_16x16x32_bf16 v[24:27], v[148:151], v[210:213], v[24:27]
	v_mfma_f32_16x16x32_bf16 v[20:23], v[160:163], v[210:213], v[20:23]
	v_mfma_f32_16x16x32_bf16 v[8:11], v[148:151], v[218:221], v[8:11]
	v_mfma_f32_16x16x32_bf16 v[4:7], v[160:163], v[218:221], v[4:7]
	v_mfma_f32_16x16x32_bf16 v[64:67], v[164:167], v[180:183], 0
	v_mfma_f32_16x16x32_bf16 v[60:63], v[172:175], v[180:183], 0
	v_mfma_f32_16x16x32_bf16 v[48:51], v[164:167], v[188:191], 0
	v_mfma_f32_16x16x32_bf16 v[44:47], v[172:175], v[188:191], 0
	v_mfma_f32_16x16x32_bf16 v[32:35], v[164:167], v[206:209], 0
	v_mfma_f32_16x16x32_bf16 v[28:31], v[172:175], v[206:209], 0
	v_mfma_f32_16x16x32_bf16 v[16:19], v[164:167], v[214:217], 0
	v_mfma_f32_16x16x32_bf16 v[12:15], v[172:175], v[214:217], 0
	v_mfma_f32_16x16x32_bf16 v[64:67], v[168:171], v[184:187], v[64:67]
	v_mfma_f32_16x16x32_bf16 v[60:63], v[176:179], v[184:187], v[60:63]
	v_mfma_f32_16x16x32_bf16 v[48:51], v[168:171], v[192:195], v[48:51]
	v_mfma_f32_16x16x32_bf16 v[44:47], v[176:179], v[192:195], v[44:47]
	v_mfma_f32_16x16x32_bf16 v[32:35], v[168:171], v[210:213], v[32:35]
	v_mfma_f32_16x16x32_bf16 v[28:31], v[176:179], v[210:213], v[28:31]
	v_mfma_f32_16x16x32_bf16 v[16:19], v[168:171], v[218:221], v[16:19]
	v_mfma_f32_16x16x32_bf16 v[12:15], v[176:179], v[218:221], v[12:15]
	s_barrier
	s_add_i32 s41, 0, 0x18000
	v_add_u32_e32 v2, s41, v157
	s_add_i32 s42, 0, 0x1c000
	ds_read_b128 v[144:147], v2
	ds_read_b128 v[148:151], v2 offset:1024
	ds_read_b128 v[152:155], v2 offset:2048
	ds_read_b128 v[160:163], v2 offset:3072
	v_add_u32_e32 v2, s42, v157
	ds_read_b128 v[164:167], v2
	ds_read_b128 v[168:171], v2 offset:1024
	ds_read_b128 v[172:175], v2 offset:2048
	ds_read_b128 v[176:179], v2 offset:3072
	s_add_u32 s22, s22, 0x40000
	s_addc_u32 s23, s23, 0
	s_mov_b32 m0, s64
	v_lshl_add_u64 v[242:243], s[22:23], 0, v[132:133]
	ds_read_b128 v[180:183], v158 offset:32768
	ds_read_b128 v[184:187], v158 offset:33792
	ds_read_b128 v[188:191], v158 offset:34816
	ds_read_b128 v[192:195], v158 offset:35840
	ds_read_b128 v[206:209], v158 offset:36864
	ds_read_b128 v[210:213], v158 offset:37888
	ds_read_b128 v[214:217], v158 offset:38912
	ds_read_b128 v[218:221], v158 offset:39936
	global_load_lds_dwordx4 v[242:243], off
	v_lshl_add_u64 v[242:243], s[22:23], 0, v[136:137]
	s_mov_b32 m0, s65
	s_nop 0
	global_load_lds_dwordx4 v[242:243], off
	s_waitcnt vmcnt(8)
	s_waitcnt lgkmcnt(0)
	s_barrier
	s_waitcnt lgkmcnt(0)
	v_mfma_f32_16x16x32_bf16 v[120:123], v[144:147], v[180:183], v[120:123]
	v_mfma_f32_16x16x32_bf16 v[116:119], v[152:155], v[180:183], v[116:119]
	v_mfma_f32_16x16x32_bf16 v[104:107], v[144:147], v[188:191], v[104:107]
	v_mfma_f32_16x16x32_bf16 v[100:103], v[152:155], v[188:191], v[100:103]
	v_mfma_f32_16x16x32_bf16 v[88:91], v[144:147], v[206:209], v[88:91]
	v_mfma_f32_16x16x32_bf16 v[84:87], v[152:155], v[206:209], v[84:87]
	v_mfma_f32_16x16x32_bf16 v[72:75], v[144:147], v[214:217], v[72:75]
	v_mfma_f32_16x16x32_bf16 v[68:71], v[152:155], v[214:217], v[68:71]
	v_mfma_f32_16x16x32_bf16 v[120:123], v[148:151], v[184:187], v[120:123]
	v_mfma_f32_16x16x32_bf16 v[116:119], v[160:163], v[184:187], v[116:119]
	v_mfma_f32_16x16x32_bf16 v[104:107], v[148:151], v[192:195], v[104:107]
	v_mfma_f32_16x16x32_bf16 v[100:103], v[160:163], v[192:195], v[100:103]
	v_mfma_f32_16x16x32_bf16 v[88:91], v[148:151], v[210:213], v[88:91]
	v_mfma_f32_16x16x32_bf16 v[84:87], v[160:163], v[210:213], v[84:87]
	v_mfma_f32_16x16x32_bf16 v[72:75], v[148:151], v[218:221], v[72:75]
	v_mfma_f32_16x16x32_bf16 v[68:71], v[160:163], v[218:221], v[68:71]
	v_mfma_f32_16x16x32_bf16 v[128:131], v[164:167], v[180:183], v[128:131]
	v_mfma_f32_16x16x32_bf16 v[124:127], v[172:175], v[180:183], v[124:127]
	v_mfma_f32_16x16x32_bf16 v[112:115], v[164:167], v[188:191], v[112:115]
	v_mfma_f32_16x16x32_bf16 v[108:111], v[172:175], v[188:191], v[108:111]
	v_mfma_f32_16x16x32_bf16 v[96:99], v[164:167], v[206:209], v[96:99]
	v_mfma_f32_16x16x32_bf16 v[92:95], v[172:175], v[206:209], v[92:95]
	v_mfma_f32_16x16x32_bf16 v[80:83], v[164:167], v[214:217], v[80:83]
	v_mfma_f32_16x16x32_bf16 v[76:79], v[172:175], v[214:217], v[76:79]
	v_mfma_f32_16x16x32_bf16 v[128:131], v[168:171], v[184:187], v[128:131]
	v_mfma_f32_16x16x32_bf16 v[124:127], v[176:179], v[184:187], v[124:127]
	v_mfma_f32_16x16x32_bf16 v[112:115], v[168:171], v[192:195], v[112:115]
	v_mfma_f32_16x16x32_bf16 v[108:111], v[176:179], v[192:195], v[108:111]
	v_mfma_f32_16x16x32_bf16 v[96:99], v[168:171], v[210:213], v[96:99]
	v_mfma_f32_16x16x32_bf16 v[92:95], v[176:179], v[210:213], v[92:95]
	v_mfma_f32_16x16x32_bf16 v[80:83], v[168:171], v[218:221], v[80:83]
	v_mfma_f32_16x16x32_bf16 v[76:79], v[176:179], v[218:221], v[76:79]
	s_barrier
	s_add_i32 s22, s41, s35
	v_lshl_add_u64 v[234:235], v[234:235], 0, s[96:97]
	s_mov_b32 m0, s22
	ds_read_b128 v[180:183], v158 offset:49152
	ds_read_b128 v[184:187], v158 offset:50176
	ds_read_b128 v[188:191], v158 offset:51200
	ds_read_b128 v[192:195], v158 offset:52224
	ds_read_b128 v[206:209], v158 offset:53248
	ds_read_b128 v[210:213], v158 offset:54272
	ds_read_b128 v[214:217], v158 offset:55296
	ds_read_b128 v[218:221], v158 offset:56320
	global_load_lds_dwordx4 v[234:235], off
	s_add_i32 m0, s22, 0x2000
	s_add_u32 s20, s20, 0x40080
	v_lshl_add_u64 v[234:235], v[236:237], 0, s[96:97]
	s_addc_u32 s21, s21, 0
	s_add_i32 s22, s42, s35
	global_load_lds_dwordx4 v[234:235], off
	v_lshl_add_u64 v[234:235], s[20:21], 0, v[134:135]
	s_mov_b32 m0, s22
	s_nop 0
	global_load_lds_dwordx4 v[234:235], off
	v_lshl_add_u64 v[234:235], s[20:21], 0, v[138:139]
	s_add_i32 m0, s22, 0x2000
	s_nop 0
	global_load_lds_dwordx4 v[234:235], off
	v_lshl_add_u64 v[234:235], v[238:239], 0, s[96:97]
	s_mov_b32 m0, s67
	s_nop 0
	global_load_lds_dwordx4 v[234:235], off
	v_lshl_add_u64 v[234:235], v[240:241], 0, s[96:97]
	s_mov_b32 m0, s68
	s_nop 0
	global_load_lds_dwordx4 v[234:235], off
	s_waitcnt vmcnt(8)
	s_waitcnt lgkmcnt(0)
	s_barrier
	s_waitcnt lgkmcnt(0)
	v_mfma_f32_16x16x32_bf16 v[56:59], v[144:147], v[180:183], v[56:59]
	v_mfma_f32_16x16x32_bf16 v[52:55], v[152:155], v[180:183], v[52:55]
	v_mfma_f32_16x16x32_bf16 v[40:43], v[144:147], v[188:191], v[40:43]
	v_mfma_f32_16x16x32_bf16 v[36:39], v[152:155], v[188:191], v[36:39]
	v_mfma_f32_16x16x32_bf16 v[24:27], v[144:147], v[206:209], v[24:27]
	v_mfma_f32_16x16x32_bf16 v[20:23], v[152:155], v[206:209], v[20:23]
	v_mfma_f32_16x16x32_bf16 v[8:11], v[144:147], v[214:217], v[8:11]
	v_mfma_f32_16x16x32_bf16 v[4:7], v[152:155], v[214:217], v[4:7]
	v_mfma_f32_16x16x32_bf16 v[56:59], v[148:151], v[184:187], v[56:59]
	v_mfma_f32_16x16x32_bf16 v[52:55], v[160:163], v[184:187], v[52:55]
	v_mfma_f32_16x16x32_bf16 v[40:43], v[148:151], v[192:195], v[40:43]
	v_mfma_f32_16x16x32_bf16 v[36:39], v[160:163], v[192:195], v[36:39]
	v_mfma_f32_16x16x32_bf16 v[24:27], v[148:151], v[210:213], v[24:27]
	v_mfma_f32_16x16x32_bf16 v[20:23], v[160:163], v[210:213], v[20:23]
	v_mfma_f32_16x16x32_bf16 v[8:11], v[148:151], v[218:221], v[8:11]
	v_mfma_f32_16x16x32_bf16 v[4:7], v[160:163], v[218:221], v[4:7]
	v_mfma_f32_16x16x32_bf16 v[64:67], v[164:167], v[180:183], v[64:67]
	v_mfma_f32_16x16x32_bf16 v[60:63], v[172:175], v[180:183], v[60:63]
	v_mfma_f32_16x16x32_bf16 v[48:51], v[164:167], v[188:191], v[48:51]
	v_mfma_f32_16x16x32_bf16 v[44:47], v[172:175], v[188:191], v[44:47]
	v_mfma_f32_16x16x32_bf16 v[32:35], v[164:167], v[206:209], v[32:35]
	v_mfma_f32_16x16x32_bf16 v[28:31], v[172:175], v[206:209], v[28:31]
	v_mfma_f32_16x16x32_bf16 v[16:19], v[164:167], v[214:217], v[16:19]
	v_mfma_f32_16x16x32_bf16 v[12:15], v[172:175], v[214:217], v[12:15]
	v_mfma_f32_16x16x32_bf16 v[64:67], v[168:171], v[184:187], v[64:67]
	v_mfma_f32_16x16x32_bf16 v[60:63], v[176:179], v[184:187], v[60:63]
	v_mfma_f32_16x16x32_bf16 v[48:51], v[168:171], v[192:195], v[48:51]
	v_mfma_f32_16x16x32_bf16 v[44:47], v[176:179], v[192:195], v[44:47]
	v_mfma_f32_16x16x32_bf16 v[32:35], v[168:171], v[210:213], v[32:35]
	v_mfma_f32_16x16x32_bf16 v[28:31], v[176:179], v[210:213], v[28:31]
	v_mfma_f32_16x16x32_bf16 v[16:19], v[168:171], v[218:221], v[16:19]
	v_mfma_f32_16x16x32_bf16 v[12:15], v[176:179], v[218:221], v[12:15]
	s_barrier
	s_add_i32 s40, s40, 2
	s_add_u32 s18, s18, 0x100
	s_addc_u32 s19, s19, 0
	s_add_u32 s26, s26, 0x100
	s_addc_u32 s27, s27, 0
	s_cmp_gt_u32 s40, 13

.LBB0_755:
	s_cmp_lg_u32 s14, 21
	s_cselect_b32 s100, 1, 0
	v_mov_b32_e32 v145, v156
	v_mov_b32_e32 v144, v1
	s_lshl_b32 s55, s16, 8
	v_lshl_add_u32 v146, v145, 4, v144
	v_add_u32_e32 v2, s69, v146
	v_cmp_gt_i32_e32 vcc, s85, v2
	s_and_saveexec_b64 s[16:17], vcc
	s_cbranch_execz .LBB0_757
	v_lshlrev_b32_e32 v164, 6, v2
	v_add_u32_e32 v164, 0x20400, v164
	ds_read_b128 v[148:151], v164
	ds_read_b128 v[152:155], v164 offset:32
	ds_read_b128 v[160:163], v164 offset:16
	ds_read_b128 v[164:167], v164 offset:48
	s_mov_b32 s15, 0x800000
	v_lshl_add_u32 v2, v2, 2, v225
	s_waitcnt lgkmcnt(0)
	v_mov_b32_e32 v168, v148
	v_mov_b32_e32 v169, v152
	v_mov_b32_e32 v152, v149
	v_mov_b32_e32 v148, v150
	v_mov_b32_e32 v149, v154
	v_mov_b32_e32 v154, v151
	v_mov_b32_e32 v150, v160
	v_mov_b32_e32 v151, v164
	v_mov_b32_e32 v164, v161
	v_mov_b32_e32 v160, v162
	v_mov_b32_e32 v161, v166
	v_mov_b32_e32 v166, v163
	v_pk_add_f32 v[152:153], v[168:169], v[152:153]
	v_pk_add_f32 v[148:149], v[148:149], v[154:155]
	v_pk_add_f32 v[150:151], v[150:151], v[164:165]
	v_pk_add_f32 v[154:155], v[160:161], v[166:167]
	v_pk_add_f32 v[148:149], v[152:153], v[148:149]
	v_pk_add_f32 v[150:151], v[150:151], v[154:155]
	s_nop 0
	v_pk_add_f32 v[148:149], v[148:149], v[150:151]
	s_nop 0
	v_add_f32_e32 v147, v148, v149
	v_fmamk_f32 v147, v147, 0x3a800000, v223
	v_mul_f32_e32 v148, 0x4b800000, v147
	v_cmp_gt_f32_e32 vcc, s15, v147
	s_nop 1
	v_cndmask_b32_e32 v147, v147, v148, vcc
	v_rsq_f32_e32 v147, v147
	s_nop 0
	v_mul_f32_e32 v148, 0x45800000, v147
	v_cndmask_b32_e32 v147, v147, v148, vcc
	ds_write_b32 v2, v147
